# P.V MFMAs in k-major order (rotating accumulators) in all attention MFMA blocks, on top of rotation + prio + counted waits
# baseline (speedup 1.0000x reference)
.LBB0_599:
	s_barrier
	s_setprio 3
	ds_read_b128 v[82:85], v188 offset:40960
	ds_read_b128 v[210:213], v188 offset:45056
	ds_read_b128 v[214:217], v189 offset:40960
	ds_read_b128 v[218:221], v189 offset:45056
	ds_read_b128 v[222:225], v190 offset:40960
	ds_read_b128 v[226:229], v190 offset:45056
	ds_read_b128 v[230:233], v191 offset:40960
	ds_read_b128 v[234:237], v191 offset:45056
	ds_read_b64_tr_b16 v[194:195], v238 offset:0
	ds_read_b64_tr_b16 v[196:197], v238 offset:2048
	ds_read_b64_tr_b16 v[198:199], v238 offset:512
	ds_read_b64_tr_b16 v[200:201], v238 offset:2560
	s_waitcnt lgkmcnt(11)
	v_mfma_f32_32x32x16_bf16 v[98:113], v[82:85], v[126:129], v[66:81]
	s_waitcnt lgkmcnt(10)
	v_mfma_f32_32x32x16_bf16 v[82:97], v[210:213], v[126:129], v[66:81]
	ds_read_b64_tr_b16 v[202:203], v238 offset:1024
	ds_read_b64_tr_b16 v[204:205], v238 offset:3072
	ds_read_b64_tr_b16 v[206:207], v238 offset:1536
	ds_read_b64_tr_b16 v[208:209], v238 offset:3584
	s_waitcnt lgkmcnt(13)
	v_mfma_f32_32x32x16_bf16 v[98:113], v[214:217], v[122:125], v[98:113]
	s_waitcnt lgkmcnt(12)
	v_mfma_f32_32x32x16_bf16 v[82:97], v[218:221], v[122:125], v[82:97]
	s_waitcnt lgkmcnt(11)
	v_mfma_f32_32x32x16_bf16 v[98:113], v[222:225], v[118:121], v[98:113]
	s_waitcnt lgkmcnt(10)
	v_mfma_f32_32x32x16_bf16 v[82:97], v[226:229], v[118:121], v[82:97]
	s_waitcnt lgkmcnt(9)
	v_mfma_f32_32x32x16_bf16 v[98:113], v[230:233], v[114:117], v[98:113]
	s_waitcnt lgkmcnt(8)
	v_mfma_f32_32x32x16_bf16 v[82:97], v[234:237], v[114:117], v[82:97]
	ds_read_b64_tr_b16 v[210:211], v238 offset:4096
	ds_read_b64_tr_b16 v[212:213], v238 offset:6144
	ds_read_b64_tr_b16 v[214:215], v238 offset:4608
	ds_read_b64_tr_b16 v[216:217], v238 offset:6656
	ds_read_b64_tr_b16 v[218:219], v238 offset:5120
	ds_read_b64_tr_b16 v[220:221], v238 offset:7168
	ds_read_b64_tr_b16 v[222:223], v238 offset:5632
	ds_read_b64_tr_b16 v[224:225], v238 offset:7680
	s_waitcnt lgkmcnt(14)
	v_mfma_f32_32x32x16_bf16 v[50:65], v[142:145], v[194:197], v[50:65]
	s_waitcnt lgkmcnt(12)
	v_mfma_f32_32x32x16_bf16 v[34:49], v[142:145], v[198:201], v[34:49]
	s_waitcnt lgkmcnt(10)
	v_mfma_f32_32x32x16_bf16 v[18:33], v[142:145], v[202:205], v[18:33]
	s_waitcnt lgkmcnt(8)
	v_mfma_f32_32x32x16_bf16 v[2:17], v[142:145], v[206:209], v[2:17]
	ds_read_b64_tr_b16 v[194:195], v238 offset:8192
	ds_read_b64_tr_b16 v[196:197], v238 offset:10240
	ds_read_b64_tr_b16 v[198:199], v238 offset:8704
	ds_read_b64_tr_b16 v[200:201], v238 offset:10752
	ds_read_b64_tr_b16 v[202:203], v238 offset:9216
	ds_read_b64_tr_b16 v[204:205], v238 offset:11264
	ds_read_b64_tr_b16 v[206:207], v238 offset:9728
	ds_read_b64_tr_b16 v[208:209], v238 offset:11776
	s_waitcnt lgkmcnt(14)
	v_mfma_f32_32x32x16_bf16 v[50:65], v[138:141], v[210:213], v[50:65]
	s_waitcnt lgkmcnt(12)
	v_mfma_f32_32x32x16_bf16 v[34:49], v[138:141], v[214:217], v[34:49]
	s_waitcnt lgkmcnt(10)
	v_mfma_f32_32x32x16_bf16 v[18:33], v[138:141], v[218:221], v[18:33]
	s_waitcnt lgkmcnt(8)
	v_mfma_f32_32x32x16_bf16 v[2:17], v[138:141], v[222:225], v[2:17]
	ds_read_b64_tr_b16 v[210:211], v238 offset:12288
	ds_read_b64_tr_b16 v[212:213], v238 offset:14336
	ds_read_b64_tr_b16 v[214:215], v238 offset:12800
	ds_read_b64_tr_b16 v[216:217], v238 offset:14848
	ds_read_b64_tr_b16 v[218:219], v238 offset:13312
	ds_read_b64_tr_b16 v[220:221], v238 offset:15360
	ds_read_b64_tr_b16 v[222:223], v238 offset:13824
	ds_read_b64_tr_b16 v[224:225], v238 offset:15872
	s_waitcnt lgkmcnt(14)
	v_mfma_f32_32x32x16_bf16 v[50:65], v[134:137], v[194:197], v[50:65]
	s_waitcnt lgkmcnt(12)
	v_mfma_f32_32x32x16_bf16 v[34:49], v[134:137], v[198:201], v[34:49]
	s_waitcnt lgkmcnt(10)
	v_mfma_f32_32x32x16_bf16 v[18:33], v[134:137], v[202:205], v[18:33]
	s_waitcnt lgkmcnt(8)
	v_mfma_f32_32x32x16_bf16 v[2:17], v[134:137], v[206:209], v[2:17]
	s_waitcnt lgkmcnt(6)
	v_mfma_f32_32x32x16_bf16 v[50:65], v[130:133], v[210:213], v[50:65]
	s_waitcnt lgkmcnt(4)
	v_mfma_f32_32x32x16_bf16 v[34:49], v[130:133], v[214:217], v[34:49]
	s_waitcnt lgkmcnt(2)
	v_mfma_f32_32x32x16_bf16 v[18:33], v[130:133], v[218:221], v[18:33]
	s_waitcnt lgkmcnt(0)
	v_mfma_f32_32x32x16_bf16 v[2:17], v[130:133], v[222:225], v[2:17]
	s_and_b64 vcc, exec, s[6:7]
	s_cbranch_vccnz .LBB0_601
	s_waitcnt vmcnt(1)

.LBB0_612:
	s_barrier
	s_setprio 3
	v_add_u32_e32 v197, s75, v193
	ds_read_b128 v[82:85], v188 offset:32768
	ds_read_b128 v[214:217], v188 offset:36864
	ds_read_b128 v[218:221], v189 offset:32768
	ds_read_b128 v[222:225], v189 offset:36864
	ds_read_b128 v[226:229], v190 offset:32768
	ds_read_b128 v[230:233], v190 offset:36864
	ds_read_b128 v[234:237], v191 offset:32768
	ds_read_b128 v[238:241], v191 offset:36864
	ds_read_b64_tr_b16 v[198:199], v197 offset:0
	ds_read_b64_tr_b16 v[200:201], v197 offset:2048
	ds_read_b64_tr_b16 v[202:203], v197 offset:512
	ds_read_b64_tr_b16 v[204:205], v197 offset:2560
	s_waitcnt lgkmcnt(11)
	v_mfma_f32_32x32x16_bf16 v[98:113], v[82:85], v[126:129], v[66:81]
	s_waitcnt lgkmcnt(10)
	v_mfma_f32_32x32x16_bf16 v[82:97], v[214:217], v[126:129], v[66:81]
	ds_read_b64_tr_b16 v[206:207], v197 offset:1024
	ds_read_b64_tr_b16 v[208:209], v197 offset:3072
	ds_read_b64_tr_b16 v[210:211], v197 offset:1536
	ds_read_b64_tr_b16 v[212:213], v197 offset:3584
	s_waitcnt lgkmcnt(13)
	v_mfma_f32_32x32x16_bf16 v[98:113], v[218:221], v[122:125], v[98:113]
	s_waitcnt lgkmcnt(12)
	v_mfma_f32_32x32x16_bf16 v[82:97], v[222:225], v[122:125], v[82:97]
	s_waitcnt lgkmcnt(11)
	v_mfma_f32_32x32x16_bf16 v[98:113], v[226:229], v[118:121], v[98:113]
	s_waitcnt lgkmcnt(10)
	v_mfma_f32_32x32x16_bf16 v[82:97], v[230:233], v[118:121], v[82:97]
	s_waitcnt lgkmcnt(9)
	v_mfma_f32_32x32x16_bf16 v[98:113], v[234:237], v[114:117], v[98:113]
	s_waitcnt lgkmcnt(8)
	v_mfma_f32_32x32x16_bf16 v[82:97], v[238:241], v[114:117], v[82:97]
	ds_read_b64_tr_b16 v[214:215], v197 offset:4096
	ds_read_b64_tr_b16 v[216:217], v197 offset:6144
	ds_read_b64_tr_b16 v[218:219], v197 offset:4608
	ds_read_b64_tr_b16 v[220:221], v197 offset:6656
	ds_read_b64_tr_b16 v[222:223], v197 offset:5120
	ds_read_b64_tr_b16 v[224:225], v197 offset:7168
	ds_read_b64_tr_b16 v[226:227], v197 offset:5632
	ds_read_b64_tr_b16 v[228:229], v197 offset:7680
	s_waitcnt lgkmcnt(14)
	v_mfma_f32_32x32x16_bf16 v[50:65], v[142:145], v[198:201], v[50:65]
	s_waitcnt lgkmcnt(12)
	v_mfma_f32_32x32x16_bf16 v[34:49], v[142:145], v[202:205], v[34:49]
	s_waitcnt lgkmcnt(10)
	v_mfma_f32_32x32x16_bf16 v[18:33], v[142:145], v[206:209], v[18:33]
	s_waitcnt lgkmcnt(8)
	v_mfma_f32_32x32x16_bf16 v[2:17], v[142:145], v[210:213], v[2:17]
	ds_read_b64_tr_b16 v[198:199], v197 offset:8192
	ds_read_b64_tr_b16 v[200:201], v197 offset:10240
	ds_read_b64_tr_b16 v[202:203], v197 offset:8704
	ds_read_b64_tr_b16 v[204:205], v197 offset:10752
	ds_read_b64_tr_b16 v[206:207], v197 offset:9216
	ds_read_b64_tr_b16 v[208:209], v197 offset:11264
	ds_read_b64_tr_b16 v[210:211], v197 offset:9728
	ds_read_b64_tr_b16 v[212:213], v197 offset:11776
	s_waitcnt lgkmcnt(14)
	v_mfma_f32_32x32x16_bf16 v[50:65], v[138:141], v[214:217], v[50:65]
	s_waitcnt lgkmcnt(12)
	v_mfma_f32_32x32x16_bf16 v[34:49], v[138:141], v[218:221], v[34:49]
	s_waitcnt lgkmcnt(10)
	v_mfma_f32_32x32x16_bf16 v[18:33], v[138:141], v[222:225], v[18:33]
	s_waitcnt lgkmcnt(8)
	v_mfma_f32_32x32x16_bf16 v[2:17], v[138:141], v[226:229], v[2:17]
	ds_read_b64_tr_b16 v[214:215], v197 offset:12288
	ds_read_b64_tr_b16 v[216:217], v197 offset:14336
	ds_read_b64_tr_b16 v[218:219], v197 offset:12800
	ds_read_b64_tr_b16 v[220:221], v197 offset:14848
	ds_read_b64_tr_b16 v[222:223], v197 offset:13312
	ds_read_b64_tr_b16 v[224:225], v197 offset:15360
	ds_read_b64_tr_b16 v[226:227], v197 offset:13824
	ds_read_b64_tr_b16 v[228:229], v197 offset:15872
	s_waitcnt lgkmcnt(14)
	v_mfma_f32_32x32x16_bf16 v[50:65], v[134:137], v[198:201], v[50:65]
	s_waitcnt lgkmcnt(12)
	v_mfma_f32_32x32x16_bf16 v[34:49], v[134:137], v[202:205], v[34:49]
	s_waitcnt lgkmcnt(10)
	v_mfma_f32_32x32x16_bf16 v[18:33], v[134:137], v[206:209], v[18:33]
	s_waitcnt lgkmcnt(8)
	v_mfma_f32_32x32x16_bf16 v[2:17], v[134:137], v[210:213], v[2:17]
	s_waitcnt lgkmcnt(6)
	v_mfma_f32_32x32x16_bf16 v[50:65], v[130:133], v[214:217], v[50:65]
	s_waitcnt lgkmcnt(4)
	v_mfma_f32_32x32x16_bf16 v[34:49], v[130:133], v[218:221], v[34:49]
	s_waitcnt lgkmcnt(2)
	v_mfma_f32_32x32x16_bf16 v[18:33], v[130:133], v[222:225], v[18:33]
	s_waitcnt lgkmcnt(0)
	v_mfma_f32_32x32x16_bf16 v[2:17], v[130:133], v[226:229], v[2:17]
	s_and_b64 vcc, exec, s[6:7]
	s_cbranch_vccnz .LBB0_614
	s_waitcnt vmcnt(1)

.LBB0_666:
	s_barrier
	s_setprio 3
	ds_read_b128 v[66:69], v189 offset:16384
	ds_read_b128 v[70:73], v189 offset:24576
	ds_read_b128 v[194:197], v190 offset:16384
	ds_read_b128 v[198:201], v190 offset:24576
	ds_read_b128 v[202:205], v191 offset:16384
	ds_read_b128 v[206:209], v191 offset:24576
	ds_read_b128 v[210:213], v192 offset:16384
	ds_read_b128 v[214:217], v192 offset:24576
	s_mov_b32 s12, s94
	s_mov_b32 s94, s8
	v_add_u32_e32 v250, s94, v185
	s_waitcnt lgkmcnt(7)
	v_mfma_f32_32x32x16_bf16 v[82:97], v[66:69], v[114:117], 0
	s_waitcnt lgkmcnt(6)
	v_mfma_f32_32x32x16_bf16 v[66:81], v[70:73], v[114:117], 0
	s_waitcnt lgkmcnt(5)
	v_mfma_f32_32x32x16_bf16 v[82:97], v[194:197], v[110:113], v[82:97]
	s_waitcnt lgkmcnt(4)
	v_mfma_f32_32x32x16_bf16 v[66:81], v[198:201], v[110:113], v[66:81]
	v_add_u32_e32 v193, v187, v168
	v_add_u32_e32 v194, v187, v170
	ds_read_b128 v[198:201], v193 offset:24576
	ds_read_b128 v[218:221], v194 offset:16384
	ds_read_b128 v[222:225], v194 offset:24576
	ds_read_b128 v[226:229], v193 offset:16384
	ds_read_b128 v[230:233], v159
	s_waitcnt lgkmcnt(8)
	v_mfma_f32_32x32x16_bf16 v[82:97], v[202:205], v[106:109], v[82:97]
	s_waitcnt lgkmcnt(7)
	v_mfma_f32_32x32x16_bf16 v[66:81], v[206:209], v[106:109], v[66:81]
	s_waitcnt lgkmcnt(6)
	v_mfma_f32_32x32x16_bf16 v[82:97], v[210:213], v[102:105], v[82:97]
	s_waitcnt lgkmcnt(5)
	v_mfma_f32_32x32x16_bf16 v[66:81], v[214:217], v[102:105], v[66:81]
	v_add_u32_e32 v195, v187, v172
	v_add_u32_e32 v196, v187, v174
	ds_read_b128 v[202:205], v195 offset:16384
	ds_read_b128 v[206:209], v195 offset:24576
	ds_read_b128 v[210:213], v196 offset:16384
	ds_read_b128 v[214:217], v196 offset:24576
	ds_read_b128 v[234:237], v159 offset:1024
	ds_read_b128 v[238:241], v159 offset:2048
	s_waitcnt lgkmcnt(7)
	v_mfma_f32_32x32x16_bf16 v[82:97], v[226:229], v[98:101], v[82:97]
	v_mfma_f32_32x32x16_bf16 v[66:81], v[198:201], v[98:101], v[66:81]
	s_waitcnt lgkmcnt(6)
	v_mfma_f32_32x32x16_bf16 v[82:97], v[218:221], v[230:233], v[82:97]
	v_mfma_f32_32x32x16_bf16 v[66:81], v[222:225], v[230:233], v[66:81]
	v_add_u32_e32 v197, v188, v177
	v_add_u32_e32 v198, v188, v179
	ds_read_b128 v[218:221], v197 offset:40960
	ds_read_b128 v[222:225], v197 offset:45056
	ds_read_b128 v[226:229], v198 offset:40960
	ds_read_b128 v[230:233], v198 offset:45056
	ds_read_b128 v[242:245], v159 offset:3072
	ds_read_b128 v[246:249], v159 offset:4096
	s_waitcnt lgkmcnt(7)
	v_mfma_f32_32x32x16_bf16 v[82:97], v[202:205], v[234:237], v[82:97]
	v_mfma_f32_32x32x16_bf16 v[66:81], v[206:209], v[234:237], v[66:81]
	s_waitcnt lgkmcnt(6)
	v_mfma_f32_32x32x16_bf16 v[82:97], v[210:213], v[238:241], v[82:97]
	v_mfma_f32_32x32x16_bf16 v[66:81], v[214:217], v[238:241], v[66:81]
	v_add_u32_e32 v199, v188, v181
	v_add_u32_e32 v200, v188, v183
	ds_read_b128 v[202:205], v199 offset:40960
	ds_read_b128 v[206:209], v199 offset:45056
	ds_read_b128 v[210:213], v200 offset:40960
	ds_read_b128 v[214:217], v200 offset:45056
	ds_read_b128 v[234:237], v159 offset:5120
	ds_read_b128 v[238:241], v159 offset:6144
	s_waitcnt lgkmcnt(7)
	v_mfma_f32_32x32x16_bf16 v[82:97], v[218:221], v[242:245], v[82:97]
	v_mfma_f32_32x32x16_bf16 v[66:81], v[222:225], v[242:245], v[66:81]
	s_waitcnt lgkmcnt(6)
	v_mfma_f32_32x32x16_bf16 v[82:97], v[226:229], v[246:249], v[82:97]
	v_mfma_f32_32x32x16_bf16 v[66:81], v[230:233], v[246:249], v[66:81]
	s_waitcnt lgkmcnt(1)
	v_mfma_f32_32x32x16_bf16 v[82:97], v[202:205], v[234:237], v[82:97]
	v_mfma_f32_32x32x16_bf16 v[66:81], v[206:209], v[234:237], v[66:81]
	s_waitcnt lgkmcnt(0)
	v_mfma_f32_32x32x16_bf16 v[82:97], v[210:213], v[238:241], v[82:97]
	v_mfma_f32_32x32x16_bf16 v[66:81], v[214:217], v[238:241], v[66:81]
	ds_read_b64_tr_b16 v[202:203], v250 offset:0
	ds_read_b64_tr_b16 v[204:205], v250 offset:2048
	ds_read_b64_tr_b16 v[206:207], v250 offset:512
	ds_read_b64_tr_b16 v[208:209], v250 offset:2560
	ds_read_b64_tr_b16 v[210:211], v250 offset:1024
	ds_read_b64_tr_b16 v[212:213], v250 offset:3072
	ds_read_b64_tr_b16 v[214:215], v250 offset:1536
	ds_read_b64_tr_b16 v[216:217], v250 offset:3584
	ds_read_b64_tr_b16 v[218:219], v250 offset:4096
	ds_read_b64_tr_b16 v[220:221], v250 offset:6144
	ds_read_b64_tr_b16 v[222:223], v250 offset:4608
	ds_read_b64_tr_b16 v[224:225], v250 offset:6656
	ds_read_b64_tr_b16 v[226:227], v250 offset:5120
	ds_read_b64_tr_b16 v[228:229], v250 offset:7168
	ds_read_b64_tr_b16 v[230:231], v250 offset:5632
	ds_read_b64_tr_b16 v[232:233], v250 offset:7680
	s_nop 0
	s_waitcnt lgkmcnt(14)
	v_mfma_f32_32x32x16_bf16 v[50:65], v[130:133], v[202:205], v[50:65]
	s_waitcnt lgkmcnt(12)
	v_mfma_f32_32x32x16_bf16 v[34:49], v[130:133], v[206:209], v[34:49]
	s_waitcnt lgkmcnt(10)
	v_mfma_f32_32x32x16_bf16 v[18:33], v[130:133], v[210:213], v[18:33]
	s_waitcnt lgkmcnt(8)
	v_mfma_f32_32x32x16_bf16 v[2:17], v[130:133], v[214:217], v[2:17]
	ds_read_b64_tr_b16 v[202:203], v250 offset:8192
	ds_read_b64_tr_b16 v[204:205], v250 offset:10240
	ds_read_b64_tr_b16 v[206:207], v250 offset:8704
	ds_read_b64_tr_b16 v[208:209], v250 offset:10752
	ds_read_b64_tr_b16 v[210:211], v250 offset:9216
	ds_read_b64_tr_b16 v[212:213], v250 offset:11264
	ds_read_b64_tr_b16 v[214:215], v250 offset:9728
	ds_read_b64_tr_b16 v[216:217], v250 offset:11776
	s_waitcnt lgkmcnt(14)
	v_mfma_f32_32x32x16_bf16 v[50:65], v[126:129], v[218:221], v[50:65]
	s_waitcnt lgkmcnt(12)
	v_mfma_f32_32x32x16_bf16 v[34:49], v[126:129], v[222:225], v[34:49]
	s_waitcnt lgkmcnt(10)
	v_mfma_f32_32x32x16_bf16 v[18:33], v[126:129], v[226:229], v[18:33]
	s_waitcnt lgkmcnt(8)
	v_mfma_f32_32x32x16_bf16 v[2:17], v[126:129], v[230:233], v[2:17]
	ds_read_b64_tr_b16 v[218:219], v250 offset:12288
	ds_read_b64_tr_b16 v[220:221], v250 offset:14336
	ds_read_b64_tr_b16 v[222:223], v250 offset:12800
	ds_read_b64_tr_b16 v[224:225], v250 offset:14848
	ds_read_b64_tr_b16 v[226:227], v250 offset:13312
	ds_read_b64_tr_b16 v[228:229], v250 offset:15360
	ds_read_b64_tr_b16 v[230:231], v250 offset:13824
	ds_read_b64_tr_b16 v[232:233], v250 offset:15872
	s_waitcnt lgkmcnt(14)
	v_mfma_f32_32x32x16_bf16 v[50:65], v[122:125], v[202:205], v[50:65]
	s_waitcnt lgkmcnt(12)
	v_mfma_f32_32x32x16_bf16 v[34:49], v[122:125], v[206:209], v[34:49]
	s_waitcnt lgkmcnt(10)
	v_mfma_f32_32x32x16_bf16 v[18:33], v[122:125], v[210:213], v[18:33]
	s_waitcnt lgkmcnt(8)
	v_mfma_f32_32x32x16_bf16 v[2:17], v[122:125], v[214:217], v[2:17]
	s_waitcnt lgkmcnt(6)
	v_mfma_f32_32x32x16_bf16 v[50:65], v[118:121], v[218:221], v[50:65]
	s_waitcnt lgkmcnt(4)
	v_mfma_f32_32x32x16_bf16 v[34:49], v[118:121], v[222:225], v[34:49]
	s_waitcnt lgkmcnt(2)
	v_mfma_f32_32x32x16_bf16 v[18:33], v[118:121], v[226:229], v[18:33]
	s_waitcnt lgkmcnt(0)
	v_mfma_f32_32x32x16_bf16 v[2:17], v[118:121], v[230:233], v[2:17]
	s_and_b64 vcc, exec, s[6:7]
	s_cbranch_vccnz .LBB0_668
	s_waitcnt vmcnt(0)

.LBB0_678:
	s_barrier
	s_setprio 3
	ds_read_b128 v[66:69], v161
	ds_read_b128 v[70:73], v161 offset:8192
	ds_read_b128 v[204:207], v163
	ds_read_b128 v[208:211], v163 offset:8192
	ds_read_b128 v[212:215], v165
	ds_read_b128 v[216:219], v165 offset:8192
	ds_read_b128 v[220:223], v167
	ds_read_b128 v[224:227], v167 offset:8192
	v_add_u32_e32 v252, s12, v185
	s_waitcnt lgkmcnt(7)
	v_mfma_f32_32x32x16_bf16 v[82:97], v[66:69], v[114:117], 0
	s_waitcnt lgkmcnt(6)
	v_mfma_f32_32x32x16_bf16 v[66:81], v[70:73], v[114:117], 0
	s_waitcnt lgkmcnt(5)
	v_mfma_f32_32x32x16_bf16 v[82:97], v[204:207], v[110:113], v[82:97]
	s_waitcnt lgkmcnt(4)
	v_mfma_f32_32x32x16_bf16 v[66:81], v[208:211], v[110:113], v[66:81]
	ds_read_b128 v[204:207], v169 offset:8192
	ds_read_b128 v[208:211], v171
	ds_read_b128 v[228:231], v171 offset:8192
	ds_read_b128 v[232:235], v169
	ds_read_b128 v[236:239], v159
	s_waitcnt lgkmcnt(8)
	v_mfma_f32_32x32x16_bf16 v[82:97], v[212:215], v[106:109], v[82:97]
	s_waitcnt lgkmcnt(7)
	v_mfma_f32_32x32x16_bf16 v[66:81], v[216:219], v[106:109], v[66:81]
	s_waitcnt lgkmcnt(6)
	v_mfma_f32_32x32x16_bf16 v[82:97], v[220:223], v[102:105], v[82:97]
	s_waitcnt lgkmcnt(5)
	v_mfma_f32_32x32x16_bf16 v[66:81], v[224:227], v[102:105], v[66:81]
	ds_read_b128 v[212:215], v173
	ds_read_b128 v[216:219], v173 offset:8192
	ds_read_b128 v[220:223], v175
	ds_read_b128 v[224:227], v175 offset:8192
	ds_read_b128 v[240:243], v159 offset:1024
	ds_read_b128 v[244:247], v159 offset:2048
	s_waitcnt lgkmcnt(7)
	v_mfma_f32_32x32x16_bf16 v[82:97], v[232:235], v[98:101], v[82:97]
	v_mfma_f32_32x32x16_bf16 v[66:81], v[204:207], v[98:101], v[66:81]
	s_waitcnt lgkmcnt(6)
	v_mfma_f32_32x32x16_bf16 v[82:97], v[208:211], v[236:239], v[82:97]
	v_mfma_f32_32x32x16_bf16 v[66:81], v[228:231], v[236:239], v[66:81]
	ds_read_b128 v[204:207], v178 offset:32768
	ds_read_b128 v[208:211], v178 offset:36864
	ds_read_b128 v[228:231], v180 offset:32768
	ds_read_b128 v[232:235], v180 offset:36864
	ds_read_b128 v[236:239], v159 offset:3072
	ds_read_b128 v[248:251], v159 offset:4096
	s_waitcnt lgkmcnt(7)
	v_mfma_f32_32x32x16_bf16 v[82:97], v[212:215], v[240:243], v[82:97]
	v_mfma_f32_32x32x16_bf16 v[66:81], v[216:219], v[240:243], v[66:81]
	s_waitcnt lgkmcnt(6)
	v_mfma_f32_32x32x16_bf16 v[82:97], v[220:223], v[244:247], v[82:97]
	v_mfma_f32_32x32x16_bf16 v[66:81], v[224:227], v[244:247], v[66:81]
	ds_read_b128 v[212:215], v182 offset:32768
	ds_read_b128 v[216:219], v182 offset:36864
	ds_read_b128 v[220:223], v184 offset:32768
	ds_read_b128 v[224:227], v184 offset:36864
	ds_read_b128 v[240:243], v159 offset:5120
	ds_read_b128 v[244:247], v159 offset:6144
	s_waitcnt lgkmcnt(7)
	v_mfma_f32_32x32x16_bf16 v[82:97], v[204:207], v[236:239], v[82:97]
	v_mfma_f32_32x32x16_bf16 v[66:81], v[208:211], v[236:239], v[66:81]
	s_waitcnt lgkmcnt(6)
	v_mfma_f32_32x32x16_bf16 v[82:97], v[228:231], v[248:251], v[82:97]
	v_mfma_f32_32x32x16_bf16 v[66:81], v[232:235], v[248:251], v[66:81]
	s_waitcnt lgkmcnt(1)
	v_mfma_f32_32x32x16_bf16 v[82:97], v[212:215], v[240:243], v[82:97]
	v_mfma_f32_32x32x16_bf16 v[66:81], v[216:219], v[240:243], v[66:81]
	s_waitcnt lgkmcnt(0)
	v_mfma_f32_32x32x16_bf16 v[82:97], v[220:223], v[244:247], v[82:97]
	v_mfma_f32_32x32x16_bf16 v[66:81], v[224:227], v[244:247], v[66:81]
	ds_read_b64_tr_b16 v[204:205], v252 offset:0
	ds_read_b64_tr_b16 v[206:207], v252 offset:2048
	ds_read_b64_tr_b16 v[208:209], v252 offset:512
	ds_read_b64_tr_b16 v[210:211], v252 offset:2560
	ds_read_b64_tr_b16 v[212:213], v252 offset:1024
	ds_read_b64_tr_b16 v[214:215], v252 offset:3072
	ds_read_b64_tr_b16 v[216:217], v252 offset:1536
	ds_read_b64_tr_b16 v[218:219], v252 offset:3584
	ds_read_b64_tr_b16 v[220:221], v252 offset:4096
	ds_read_b64_tr_b16 v[222:223], v252 offset:6144
	ds_read_b64_tr_b16 v[224:225], v252 offset:4608
	ds_read_b64_tr_b16 v[226:227], v252 offset:6656
	ds_read_b64_tr_b16 v[228:229], v252 offset:5120
	ds_read_b64_tr_b16 v[230:231], v252 offset:7168
	ds_read_b64_tr_b16 v[232:233], v252 offset:5632
	ds_read_b64_tr_b16 v[234:235], v252 offset:7680
	s_nop 0
	s_waitcnt lgkmcnt(14)
	v_mfma_f32_32x32x16_bf16 v[50:65], v[130:133], v[204:207], v[50:65]
	s_waitcnt lgkmcnt(12)
	v_mfma_f32_32x32x16_bf16 v[34:49], v[130:133], v[208:211], v[34:49]
	s_waitcnt lgkmcnt(10)
	v_mfma_f32_32x32x16_bf16 v[18:33], v[130:133], v[212:215], v[18:33]
	s_waitcnt lgkmcnt(8)
	v_mfma_f32_32x32x16_bf16 v[2:17], v[130:133], v[216:219], v[2:17]
	ds_read_b64_tr_b16 v[204:205], v252 offset:8192
	ds_read_b64_tr_b16 v[206:207], v252 offset:10240
	ds_read_b64_tr_b16 v[208:209], v252 offset:8704
	ds_read_b64_tr_b16 v[210:211], v252 offset:10752
	ds_read_b64_tr_b16 v[212:213], v252 offset:9216
	ds_read_b64_tr_b16 v[214:215], v252 offset:11264
	ds_read_b64_tr_b16 v[216:217], v252 offset:9728
	ds_read_b64_tr_b16 v[218:219], v252 offset:11776
	s_waitcnt lgkmcnt(14)
	v_mfma_f32_32x32x16_bf16 v[50:65], v[126:129], v[220:223], v[50:65]
	s_waitcnt lgkmcnt(12)
	v_mfma_f32_32x32x16_bf16 v[34:49], v[126:129], v[224:227], v[34:49]
	s_waitcnt lgkmcnt(10)
	v_mfma_f32_32x32x16_bf16 v[18:33], v[126:129], v[228:231], v[18:33]
	s_waitcnt lgkmcnt(8)
	v_mfma_f32_32x32x16_bf16 v[2:17], v[126:129], v[232:235], v[2:17]
	ds_read_b64_tr_b16 v[220:221], v252 offset:12288
	ds_read_b64_tr_b16 v[222:223], v252 offset:14336
	ds_read_b64_tr_b16 v[224:225], v252 offset:12800
	ds_read_b64_tr_b16 v[226:227], v252 offset:14848
	ds_read_b64_tr_b16 v[228:229], v252 offset:13312
	ds_read_b64_tr_b16 v[230:231], v252 offset:15360
	ds_read_b64_tr_b16 v[232:233], v252 offset:13824
	ds_read_b64_tr_b16 v[234:235], v252 offset:15872
	s_waitcnt lgkmcnt(14)
	v_mfma_f32_32x32x16_bf16 v[50:65], v[122:125], v[204:207], v[50:65]
	s_waitcnt lgkmcnt(12)
	v_mfma_f32_32x32x16_bf16 v[34:49], v[122:125], v[208:211], v[34:49]
	s_waitcnt lgkmcnt(10)
	v_mfma_f32_32x32x16_bf16 v[18:33], v[122:125], v[212:215], v[18:33]
	s_waitcnt lgkmcnt(8)
	v_mfma_f32_32x32x16_bf16 v[2:17], v[122:125], v[216:219], v[2:17]
	s_waitcnt lgkmcnt(6)
	v_mfma_f32_32x32x16_bf16 v[50:65], v[118:121], v[220:223], v[50:65]
	s_waitcnt lgkmcnt(4)
	v_mfma_f32_32x32x16_bf16 v[34:49], v[118:121], v[224:227], v[34:49]
	s_waitcnt lgkmcnt(2)
	v_mfma_f32_32x32x16_bf16 v[18:33], v[118:121], v[228:231], v[18:33]
	s_waitcnt lgkmcnt(0)
	v_mfma_f32_32x32x16_bf16 v[2:17], v[118:121], v[232:235], v[2:17]
	s_and_b64 vcc, exec, s[6:7]
	s_cbranch_vccnz .LBB0_680
	s_waitcnt vmcnt(0)
